# gu phases: rstd loads and reduction moved from SwiGLU epilogue into the peeled first K iteration
# speedup vs baseline: 1.0109x; 1.0012x over previous
;     __device__ __forceinline__ bool next(int i, pg8::Unit& u) const { if (!base.next(i >> 2, u)) return false; u.sub = i & 3; return true; }
; template <class Epi, class Sched, bool ALIGN_EPI = false, bool SP2 = false>
; __device__ __forceinline__ void gemm_phase(PG8_LAS unsigned char* lds, const Gemm g, const Sched& S, const Epi& E, const int tid) {
;     ...
;         const bool has_next = S.next(ui + 1, nxt);
; __device__ __forceinline__ void rstd8(const float* ssq, int row0, int fq, float (&rs)[8]) {
;     f32x4 pr[8];
; #pragma unroll
;     for (int i = 0; i < 8; ++i) pr[i] = *(const f32x4*)(ssq + (size_t)(row0 + (i >> 2) * 128 + (i & 3) * 16) * 16 + 4 * fq);
.LBB0_332:
	v_lshl_add_u32 v10, s36, 8, v1
	v_mov_b32_e32 v11, 0
	v_lshlrev_b32_e32 v10, 6, v10
	v_mov_b32_e32 v14, 0x2000
	v_mov_b32_e32 v15, 0
	v_lshl_add_u64 v[12:13], v[140:141], 0, v[10:11]
	v_lshl_add_u64 v[14:15], v[12:13], 0, v[14:15]
	global_load_dwordx4 v[6:9], v[12:13], off
	global_load_dwordx4 v[18:21], v[12:13], off offset:1024
	global_load_dwordx4 v[22:25], v[12:13], off offset:2048
	global_load_dwordx4 v[34:37], v[12:13], off offset:3072
	global_load_dwordx4 v[38:41], v[14:15], off
	global_load_dwordx4 v[50:53], v[14:15], off offset:1024
	global_load_dwordx4 v[54:57], v[14:15], off offset:2048
	global_load_dwordx4 v[58:61], v[14:15], off offset:3072
	s_add_i32 s61, s61, 1
	s_mul_i32 s2, s61, s57
	s_mul_hi_u32 s3, s61, s44
	s_add_i32 s3, s3, s2
	s_mul_i32 s2, s61, s44
	s_add_u32 s30, s2, s25
	s_addc_u32 s31, s3, s45
	v_cmp_gt_i64_e32 vcc, s[30:31], v[148:149]
	v_cmp_lt_i64_e64 s[2:3], s[30:31], v[146:147]
	s_cbranch_vccnz .LBB0_338
	s_ashr_i32 s15, s30, 31
	s_lshr_b32 s15, s15, 29
	s_add_i32 s15, s30, s15
	s_and_b32 s18, s15, -8
	s_sub_i32 s18, s30, s18
	s_cmp_gt_i32 s18, 3
	s_mov_b64 s[26:27], -1
	s_cbranch_scc0 .LBB0_335
	s_mul_i32 s19, s18, 0x215
	s_add_i32 s19, s19, 4
	s_mov_b64 s[26:27], 0

; #define PG8_STAGE(bufoff, gbase, voff) do { _Pragma("unroll") for (int _i = 0; _i < 2; ++_i) \
;         __builtin_amdgcn_global_load_lds((const unsigned*)((const char*)(gbase) + (voff)[_i]), (PG8_LAS unsigned*)(lds + (bufoff) + ldsw + _i * 8192), 16, 0, 0); } while (0)
; #define PG8_LDA(dst, b, h) do { _Pragma("unroll") for (int m = 0; m < 4; ++m) _Pragma("unroll") for (int k = 0; k < 2; ++k) dst[m][k] = *(const PG8_LAS bf16x8*)(lds + PG8_SA(b, h) + aoff + m * 2048 + k * 1024); } while (0)
; #define PG8_LDB(dst, b, h) do { _Pragma("unroll") for (int n = 0; n < 2; ++n) _Pragma("unroll") for (int k = 0; k < 2; ++k) dst[n][k] = *(const PG8_LAS bf16x8*)(lds + PG8_SB(b, h) + boff + n * 2048 + k * 1024); } while (0)
; #define PG8_MMA(ai, bj, At, Bt) do { __builtin_amdgcn_s_setprio(1); _Pragma("unroll") for (int m = 0; m < 4; ++m) _Pragma("unroll") for (int n = 0; n < 2; ++n) _Pragma("unroll") for (int k = 0; k < 2; ++k) \
;         acc[ai][bj][m][n] = __builtin_amdgcn_mfma_f32_16x16x32_bf16(Bt[n][k], At[m][k], acc[ai][bj][m][n], 0, 0, 0); __builtin_amdgcn_s_setprio(0); } while (0)
; #define PG8_WAIT_V(n) asm volatile("s_waitcnt vmcnt(" #n ")" ::: "memory")
; #define PG8_WAIT_L(n) asm volatile("s_waitcnt lgkmcnt(" #n ")" ::: "memory")
; #define PG8_BAR __builtin_amdgcn_s_barrier()
; #define PG8_SCHED __builtin_amdgcn_sched_barrier(0)
; template <class Epi, class Sched, bool ALIGN_EPI = false, bool SP2 = false>
; __device__ __forceinline__ void gemm_phase(PG8_LAS unsigned char* lds, const Gemm g, const Sched& S, const Epi& E, const int tid) {
;     ...
;             PG8_LDB(B0, 0, 0); PG8_LDB(B1, 0, 1); PG8_SCHED; PG8_LDA(At, 0, 0); PG8_STAGE(PG8_SA(1, 1), a1 + hstep, voffA);
;             PG8_WAIT_V(8); PG8_WAIT_L(0); PG8_BAR; PG8_MMA(0, 0, At, B0); PG8_MMA(0, 1, At, B1); PG8_BAR; PG8_SCHED;
.LBB0_338:
	s_ashr_i32 s29, s28, 31
	s_lshl_b64 s[18:19], s[28:29], 19
	s_add_u32 s30, s46, s18
	s_addc_u32 s31, s47, s19
	s_and_b64 s[18:19], s[2:3], exec
	s_cselect_b32 s29, s31, s41
	s_cselect_b32 s62, s30, s40
	s_ashr_i32 s27, s26, 31
	s_lshl_b64 s[18:19], s[26:27], 19
	s_add_u32 s34, s48, s18
	s_addc_u32 s35, s49, s19
	s_and_b64 s[18:19], s[2:3], exec
	s_cselect_b32 s27, s35, s39
	s_cselect_b32 s63, s34, s38
	s_add_u32 s64, s38, 0x100
	s_addc_u32 s65, s39, 0
	s_add_u32 s38, s40, 0x40080
	s_addc_u32 s39, s41, 0
	s_mov_b32 s66, -2
	ds_read_b128 v[150:153], v161
	ds_read_b128 v[172:175], v161 offset:1024
	ds_read_b128 v[176:179], v161 offset:2048
	ds_read_b128 v[180:183], v161 offset:3072
	ds_read_b128 v[184:187], v163
	ds_read_b128 v[192:195], v163 offset:1024
	ds_read_b128 v[196:199], v163 offset:2048
	ds_read_b128 v[200:203], v163 offset:3072
	s_add_u32 s15, s38, 0xfffc0080
	s_addc_u32 s18, s39, -1
	s_cmp_eq_u32 s66, 12
	s_cselect_b32 s43, s29, s18
	s_cselect_b32 s42, s62, s15
	s_cselect_b32 s41, s27, s65
	s_cselect_b32 s40, s63, s64
	v_lshl_add_u64 v[154:155], s[38:39], 0, v[144:145]
	s_add_i32 m0, s51, 0xc000
	ds_read_b128 v[204:207], v167
	ds_read_b128 v[208:211], v167 offset:1024
	ds_read_b128 v[212:215], v167 offset:2048
	ds_read_b128 v[216:219], v167 offset:3072
	ds_read_b128 v[220:223], v167 offset:4096
	ds_read_b128 v[224:227], v167 offset:5120
	ds_read_b128 v[228:231], v167 offset:6144
	ds_read_b128 v[232:235], v167 offset:7168
	global_load_lds_dwordx4 v[154:155], off
	v_lshl_add_u64 v[154:155], s[38:39], 0, v[142:143]
	s_add_i32 m0, s51, 0xe000
	s_nop 0
	global_load_lds_dwordx4 v[154:155], off
	s_waitcnt vmcnt(16)
	s_waitcnt lgkmcnt(0)
	s_barrier
	s_setprio 1
	s_waitcnt lgkmcnt(0)
	v_mfma_f32_16x16x32_bf16 v[126:129], v[150:153], v[204:207], 0
	v_mfma_f32_16x16x32_bf16 v[122:125], v[176:179], v[204:207], 0
	v_mfma_f32_16x16x32_bf16 v[110:113], v[150:153], v[212:215], 0
	v_mfma_f32_16x16x32_bf16 v[106:109], v[176:179], v[212:215], 0
	v_mfma_f32_16x16x32_bf16 v[94:97], v[150:153], v[220:223], 0
	v_mfma_f32_16x16x32_bf16 v[90:93], v[176:179], v[220:223], 0
	v_mfma_f32_16x16x32_bf16 v[78:81], v[150:153], v[228:231], 0
	v_mfma_f32_16x16x32_bf16 v[74:77], v[176:179], v[228:231], 0
	v_mfma_f32_16x16x32_bf16 v[126:129], v[172:175], v[208:211], v[126:129]
	v_mfma_f32_16x16x32_bf16 v[122:125], v[180:183], v[208:211], v[122:125]
	v_mfma_f32_16x16x32_bf16 v[110:113], v[172:175], v[216:219], v[110:113]
	v_mfma_f32_16x16x32_bf16 v[106:109], v[180:183], v[216:219], v[106:109]
	v_mfma_f32_16x16x32_bf16 v[94:97], v[172:175], v[224:227], v[94:97]
	v_mfma_f32_16x16x32_bf16 v[90:93], v[180:183], v[224:227], v[90:93]
	v_mfma_f32_16x16x32_bf16 v[78:81], v[172:175], v[232:235], v[78:81]
	v_mfma_f32_16x16x32_bf16 v[74:77], v[180:183], v[232:235], v[74:77]
	s_setprio 0
	s_setprio 1
	v_mfma_f32_16x16x32_bf16 v[118:121], v[184:187], v[204:207], 0
	v_mfma_f32_16x16x32_bf16 v[114:117], v[196:199], v[204:207], 0
	v_mfma_f32_16x16x32_bf16 v[102:105], v[184:187], v[212:215], 0
	v_mfma_f32_16x16x32_bf16 v[98:101], v[196:199], v[212:215], 0
	v_mfma_f32_16x16x32_bf16 v[86:89], v[184:187], v[220:223], 0
	v_mfma_f32_16x16x32_bf16 v[82:85], v[196:199], v[220:223], 0
	v_mfma_f32_16x16x32_bf16 v[70:73], v[184:187], v[228:231], 0
	v_mfma_f32_16x16x32_bf16 v[66:69], v[196:199], v[228:231], 0
	v_mfma_f32_16x16x32_bf16 v[118:121], v[192:195], v[208:211], v[118:121]
	v_mfma_f32_16x16x32_bf16 v[114:117], v[200:203], v[208:211], v[114:117]
	v_mfma_f32_16x16x32_bf16 v[102:105], v[192:195], v[216:219], v[102:105]
	v_mfma_f32_16x16x32_bf16 v[98:101], v[200:203], v[216:219], v[98:101]
	v_mfma_f32_16x16x32_bf16 v[86:89], v[192:195], v[224:227], v[86:89]
	v_mfma_f32_16x16x32_bf16 v[82:85], v[200:203], v[224:227], v[82:85]
	v_mfma_f32_16x16x32_bf16 v[70:73], v[192:195], v[232:235], v[70:73]
	v_mfma_f32_16x16x32_bf16 v[66:69], v[200:203], v[232:235], v[66:69]
	s_setprio 0
	s_barrier
	s_add_i32 s15, s58, s50
	v_lshl_add_u64 v[154:155], s[40:41], 0, v[132:133]
	s_mov_b32 m0, s15
	ds_read_b128 v[204:207], v167 offset:16384
	ds_read_b128 v[208:211], v167 offset:17408
	ds_read_b128 v[212:215], v167 offset:18432
	ds_read_b128 v[216:219], v167 offset:19456
	ds_read_b128 v[220:223], v167 offset:20480
	ds_read_b128 v[224:227], v167 offset:21504
	ds_read_b128 v[228:231], v167 offset:22528
	ds_read_b128 v[232:235], v167 offset:23552
	global_load_lds_dwordx4 v[154:155], off
	s_add_i32 m0, s15, 0x2000
	s_add_u32 s18, s40, 0x40000
	v_lshl_add_u64 v[158:159], s[40:41], 0, v[136:137]
	s_addc_u32 s19, s41, 0
	s_add_i32 s15, s59, s50
	global_load_lds_dwordx4 v[158:159], off
	v_lshl_add_u64 v[164:165], s[18:19], 0, v[132:133]
	s_mov_b32 m0, s15
	v_lshl_add_u64 v[168:169], s[42:43], 0, v[134:135]
	global_load_lds_dwordx4 v[164:165], off
	v_lshl_add_u64 v[164:165], s[18:19], 0, v[136:137]
	s_add_i32 m0, s15, 0x2000
	s_nop 0
	global_load_lds_dwordx4 v[164:165], off
	v_lshl_add_u64 v[164:165], s[42:43], 0, v[130:131]
	s_mov_b32 m0, s51
	s_nop 0
	global_load_lds_dwordx4 v[164:165], off
	s_mov_b32 m0, s52
	s_nop 0
	global_load_lds_dwordx4 v[168:169], off
	s_waitcnt vmcnt(8)
; #define PG8_MMA(ai, bj, At, Bt) do { __builtin_amdgcn_s_setprio(1); _Pragma("unroll") for (int m = 0; m < 4; ++m) _Pragma("unroll") for (int n = 0; n < 2; ++n) _Pragma("unroll") for (int k = 0; k < 2; ++k) \
;         acc[ai][bj][m][n] = __builtin_amdgcn_mfma_f32_16x16x32_bf16(Bt[n][k], At[m][k], acc[ai][bj][m][n], 0, 0, 0); __builtin_amdgcn_s_setprio(0); } while (0)
; #define PG8_WAIT_V(n) asm volatile("s_waitcnt vmcnt(" #n ")" ::: "memory")
; #define PG8_WAIT_L(n) asm volatile("s_waitcnt lgkmcnt(" #n ")" ::: "memory")
; #define PG8_BAR __builtin_amdgcn_s_barrier()
; #define PG8_SCHED __builtin_amdgcn_sched_barrier(0)
; __device__ __forceinline__ float xsum16(float s) { const auto r = __builtin_amdgcn_permlane16_swap(__float_as_uint(s), __float_as_uint(s), false, false); return __uint_as_float(r[0]) + __uint_as_float(r[1]); }
; __device__ __forceinline__ float xsum32(float s) { const auto r = __builtin_amdgcn_permlane32_swap(__float_as_uint(s), __float_as_uint(s), false, false); return __uint_as_float(r[0]) + __uint_as_float(r[1]); }
; template <class Epi, class Sched, bool ALIGN_EPI = false, bool SP2 = false>
; __device__ __forceinline__ void gemm_phase(PG8_LAS unsigned char* lds, const Gemm g, const Sched& S, const Epi& E, const int tid) {
;     ...
;             PG8_WAIT_V(8); PG8_WAIT_L(0); PG8_BAR; PG8_MMA(1, 0, At, B0); PG8_MMA(1, 1, At, B1); PG8_BAR; PG8_SCHED;
; __device__ __forceinline__ void rstd8(const float* ssq, int row0, int fq, float (&rs)[8]) {
;     ...
; #pragma unroll
;     for (int i = 0; i < 8; ++i) { float s = (pr[i][0] + pr[i][1]) + (pr[i][2] + pr[i][3]); s = xsum16(s); s = xsum32(s); rs[i] = __builtin_amdgcn_rsqf(s * (1.0f / DM) + NORM_EPS); }
	v_add_f32_e32 v6, v6, v7
	v_add_f32_e32 v18, v18, v19
	v_add_f32_e32 v22, v22, v23
	v_add_f32_e32 v34, v34, v35
	v_add_f32_e32 v38, v38, v39
	v_add_f32_e32 v50, v50, v51
	v_add_f32_e32 v54, v54, v55
	v_add_f32_e32 v58, v58, v59
	v_add_f32_e32 v8, v8, v9
	v_add_f32_e32 v20, v20, v21
	v_add_f32_e32 v24, v24, v25
	v_add_f32_e32 v36, v36, v37
	v_add_f32_e32 v40, v40, v41
	v_add_f32_e32 v52, v52, v53
	v_add_f32_e32 v56, v56, v57
	v_add_f32_e32 v60, v60, v61
	v_add_f32_e32 v243, v6, v8
	v_add_f32_e32 v244, v18, v20
	v_add_f32_e32 v245, v22, v24
	v_add_f32_e32 v246, v34, v36
	v_add_f32_e32 v247, v38, v40
	v_add_f32_e32 v248, v50, v52
	v_add_f32_e32 v249, v54, v56
	v_add_f32_e32 v250, v58, v60
	v_mov_b32_e32 v6, v243
	v_mov_b32_e32 v18, v244
	v_mov_b32_e32 v22, v245
	v_mov_b32_e32 v34, v246
	v_mov_b32_e32 v38, v247
	v_mov_b32_e32 v50, v248
	v_mov_b32_e32 v54, v249
	v_mov_b32_e32 v58, v250
	v_permlane16_swap_b32_e32 v243, v6
	v_permlane16_swap_b32_e32 v244, v18
	v_permlane16_swap_b32_e32 v245, v22
	v_permlane16_swap_b32_e32 v246, v34
	v_permlane16_swap_b32_e32 v247, v38
	v_permlane16_swap_b32_e32 v248, v50
	v_permlane16_swap_b32_e32 v249, v54
	v_permlane16_swap_b32_e32 v250, v58
	v_add_f32_e32 v243, v243, v6
	v_add_f32_e32 v244, v244, v18
	v_add_f32_e32 v245, v245, v22
	v_add_f32_e32 v246, v246, v34
	v_add_f32_e32 v247, v247, v38
	v_add_f32_e32 v248, v248, v50
	v_add_f32_e32 v249, v249, v54
	v_add_f32_e32 v250, v250, v58
	v_mov_b32_e32 v6, v243
	v_mov_b32_e32 v18, v244
	v_mov_b32_e32 v22, v245
	v_mov_b32_e32 v34, v246
	v_mov_b32_e32 v38, v247
	v_mov_b32_e32 v50, v248
	v_mov_b32_e32 v54, v249
	v_mov_b32_e32 v58, v250
	v_permlane32_swap_b32_e32 v243, v6
	v_permlane32_swap_b32_e32 v244, v18
	v_permlane32_swap_b32_e32 v245, v22
	v_permlane32_swap_b32_e32 v246, v34
	v_permlane32_swap_b32_e32 v247, v38
	v_permlane32_swap_b32_e32 v248, v50
	v_permlane32_swap_b32_e32 v249, v54
	v_permlane32_swap_b32_e32 v250, v58
	v_add_f32_e32 v243, v243, v6
	v_add_f32_e32 v244, v244, v18
	v_add_f32_e32 v245, v245, v22
	v_add_f32_e32 v246, v246, v34
	v_add_f32_e32 v247, v247, v38
	v_add_f32_e32 v248, v248, v50
	v_add_f32_e32 v249, v249, v54
	v_add_f32_e32 v250, v250, v58
	v_fmamk_f32 v243, v243, 0x3a800000, v171
	v_fmamk_f32 v244, v244, 0x3a800000, v171
	v_fmamk_f32 v245, v245, 0x3a800000, v171
	v_fmamk_f32 v246, v246, 0x3a800000, v171
	v_fmamk_f32 v247, v247, 0x3a800000, v171
	v_fmamk_f32 v248, v248, 0x3a800000, v171
	v_fmamk_f32 v249, v249, 0x3a800000, v171
	v_fmamk_f32 v250, v250, 0x3a800000, v171
	v_rsq_f32_e32 v243, v243
	v_rsq_f32_e32 v244, v244
	v_rsq_f32_e32 v245, v245
	v_rsq_f32_e32 v246, v246
	v_rsq_f32_e32 v247, v247
	v_rsq_f32_e32 v248, v248
	v_rsq_f32_e32 v249, v249
	v_rsq_f32_e32 v250, v250
	s_waitcnt lgkmcnt(0)
	s_barrier
	s_setprio 1
	s_waitcnt lgkmcnt(0)
	v_mfma_f32_16x16x32_bf16 v[62:65], v[150:153], v[204:207], 0
	v_mfma_f32_16x16x32_bf16 v[58:61], v[176:179], v[204:207], 0
	v_mfma_f32_16x16x32_bf16 v[46:49], v[150:153], v[212:215], 0
	v_mfma_f32_16x16x32_bf16 v[42:45], v[176:179], v[212:215], 0
	v_mfma_f32_16x16x32_bf16 v[30:33], v[150:153], v[220:223], 0
	v_mfma_f32_16x16x32_bf16 v[26:29], v[176:179], v[220:223], 0
	v_mfma_f32_16x16x32_bf16 v[14:17], v[150:153], v[228:231], 0
	v_mfma_f32_16x16x32_bf16 v[10:13], v[176:179], v[228:231], 0
	v_mfma_f32_16x16x32_bf16 v[62:65], v[172:175], v[208:211], v[62:65]
	v_mfma_f32_16x16x32_bf16 v[58:61], v[180:183], v[208:211], v[58:61]
	v_mfma_f32_16x16x32_bf16 v[46:49], v[172:175], v[216:219], v[46:49]
	v_mfma_f32_16x16x32_bf16 v[42:45], v[180:183], v[216:219], v[42:45]
	v_mfma_f32_16x16x32_bf16 v[30:33], v[172:175], v[224:227], v[30:33]
	v_mfma_f32_16x16x32_bf16 v[26:29], v[180:183], v[224:227], v[26:29]
	v_mfma_f32_16x16x32_bf16 v[14:17], v[172:175], v[232:235], v[14:17]
	v_mfma_f32_16x16x32_bf16 v[10:13], v[180:183], v[232:235], v[10:13]
	s_setprio 0
	s_setprio 1
	v_mfma_f32_16x16x32_bf16 v[54:57], v[184:187], v[204:207], 0
	v_mfma_f32_16x16x32_bf16 v[50:53], v[196:199], v[204:207], 0
	v_mfma_f32_16x16x32_bf16 v[38:41], v[184:187], v[212:215], 0
	v_mfma_f32_16x16x32_bf16 v[34:37], v[196:199], v[212:215], 0
	v_mfma_f32_16x16x32_bf16 v[22:25], v[184:187], v[220:223], 0
	v_mfma_f32_16x16x32_bf16 v[18:21], v[196:199], v[220:223], 0
	v_mfma_f32_16x16x32_bf16 v[6:9], v[184:187], v[228:231], 0
	v_mfma_f32_16x16x32_bf16 v[2:5], v[196:199], v[228:231], 0
	v_mfma_f32_16x16x32_bf16 v[54:57], v[192:195], v[208:211], v[54:57]
	v_mfma_f32_16x16x32_bf16 v[50:53], v[200:203], v[208:211], v[50:53]
	v_mfma_f32_16x16x32_bf16 v[38:41], v[192:195], v[216:219], v[38:41]
	v_mfma_f32_16x16x32_bf16 v[34:37], v[200:203], v[216:219], v[34:37]
	v_mfma_f32_16x16x32_bf16 v[22:25], v[192:195], v[224:227], v[22:25]
	v_mfma_f32_16x16x32_bf16 v[18:21], v[200:203], v[224:227], v[18:21]
	v_mfma_f32_16x16x32_bf16 v[6:9], v[192:195], v[232:235], v[6:9]
	v_mfma_f32_16x16x32_bf16 v[2:5], v[200:203], v[232:235], v[2:5]
	s_setprio 0
	s_barrier
	s_add_i32 s15, 0, 0x18000
	v_add_u32_e32 v156, s15, v157
	s_add_i32 s67, 0, 0x1c000
	ds_read_b128 v[150:153], v156
	ds_read_b128 v[172:175], v156 offset:1024
	ds_read_b128 v[176:179], v156 offset:2048
	ds_read_b128 v[180:183], v156 offset:3072
	v_add_u32_e32 v156, s67, v157
	ds_read_b128 v[184:187], v156
	ds_read_b128 v[192:195], v156 offset:1024
	ds_read_b128 v[196:199], v156 offset:2048
	ds_read_b128 v[200:203], v156 offset:3072
	s_add_u32 s18, s42, 0x40000
	s_addc_u32 s19, s43, 0
	s_mov_b32 m0, s53
	v_lshl_add_u64 v[188:189], s[18:19], 0, v[130:131]
	ds_read_b128 v[204:207], v167 offset:32768
	ds_read_b128 v[208:211], v167 offset:33792
	ds_read_b128 v[212:215], v167 offset:34816
	ds_read_b128 v[216:219], v167 offset:35840
	ds_read_b128 v[220:223], v167 offset:36864
	ds_read_b128 v[224:227], v167 offset:37888
	ds_read_b128 v[228:231], v167 offset:38912
	ds_read_b128 v[232:235], v167 offset:39936
	global_load_lds_dwordx4 v[188:189], off
	v_lshl_add_u64 v[188:189], s[18:19], 0, v[134:135]
	s_mov_b32 m0, s54
	s_nop 0
	global_load_lds_dwordx4 v[188:189], off
	s_waitcnt vmcnt(8)
	s_waitcnt lgkmcnt(0)
	s_barrier
; #define PG8_STAGE(bufoff, gbase, voff) do { _Pragma("unroll") for (int _i = 0; _i < 2; ++_i) \
;         __builtin_amdgcn_global_load_lds((const unsigned*)((const char*)(gbase) + (voff)[_i]), (PG8_LAS unsigned*)(lds + (bufoff) + ldsw + _i * 8192), 16, 0, 0); } while (0)
; #define PG8_LDA(dst, b, h) do { _Pragma("unroll") for (int m = 0; m < 4; ++m) _Pragma("unroll") for (int k = 0; k < 2; ++k) dst[m][k] = *(const PG8_LAS bf16x8*)(lds + PG8_SA(b, h) + aoff + m * 2048 + k * 1024); } while (0)
; #define PG8_LDB(dst, b, h) do { _Pragma("unroll") for (int n = 0; n < 2; ++n) _Pragma("unroll") for (int k = 0; k < 2; ++k) dst[n][k] = *(const PG8_LAS bf16x8*)(lds + PG8_SB(b, h) + boff + n * 2048 + k * 1024); } while (0)
; #define PG8_MMA(ai, bj, At, Bt) do { __builtin_amdgcn_s_setprio(1); _Pragma("unroll") for (int m = 0; m < 4; ++m) _Pragma("unroll") for (int n = 0; n < 2; ++n) _Pragma("unroll") for (int k = 0; k < 2; ++k) \
;         acc[ai][bj][m][n] = __builtin_amdgcn_mfma_f32_16x16x32_bf16(Bt[n][k], At[m][k], acc[ai][bj][m][n], 0, 0, 0); __builtin_amdgcn_s_setprio(0); } while (0)
; #define PG8_WAIT_V(n) asm volatile("s_waitcnt vmcnt(" #n ")" ::: "memory")
; #define PG8_WAIT_L(n) asm volatile("s_waitcnt lgkmcnt(" #n ")" ::: "memory")
; #define PG8_BAR __builtin_amdgcn_s_barrier()
; #define PG8_SCHED __builtin_amdgcn_sched_barrier(0)
; template <class Epi, class Sched, bool ALIGN_EPI = false, bool SP2 = false>
; __device__ __forceinline__ void gemm_phase(PG8_LAS unsigned char* lds, const Gemm g, const Sched& S, const Epi& E, const int tid) {
;     ...
;             PG8_LDB(B0, 1, 0); PG8_LDB(B1, 1, 1); PG8_SCHED; PG8_LDA(At, 1, 0); PG8_STAGE(PG8_SA(0, 1), a2 + hstep, voffA);
;             PG8_WAIT_V(8); PG8_WAIT_L(0); PG8_BAR; PG8_MMA(0, 0, At, B0); PG8_MMA(0, 1, At, B1); PG8_BAR; PG8_SCHED;
;             PG8_LDA(At, 1, 1); PG8_STAGE(PG8_SB(1, 0), b3, voffB); PG8_STAGE(PG8_SB(1, 1), b3 + hstep, voffB); PG8_STAGE(PG8_SA(1, 0), a3, voffA);
;             PG8_WAIT_V(8); PG8_WAIT_L(0); PG8_BAR; PG8_MMA(1, 0, At, B0); PG8_MMA(1, 1, At, B1); PG8_BAR; PG8_SCHED;
	s_setprio 1
	s_waitcnt lgkmcnt(0)
	v_mfma_f32_16x16x32_bf16 v[126:129], v[150:153], v[204:207], v[126:129]
	v_mfma_f32_16x16x32_bf16 v[122:125], v[176:179], v[204:207], v[122:125]
	v_mfma_f32_16x16x32_bf16 v[110:113], v[150:153], v[212:215], v[110:113]
	v_mfma_f32_16x16x32_bf16 v[106:109], v[176:179], v[212:215], v[106:109]
	v_mfma_f32_16x16x32_bf16 v[94:97], v[150:153], v[220:223], v[94:97]
	v_mfma_f32_16x16x32_bf16 v[90:93], v[176:179], v[220:223], v[90:93]
	v_mfma_f32_16x16x32_bf16 v[78:81], v[150:153], v[228:231], v[78:81]
	v_mfma_f32_16x16x32_bf16 v[74:77], v[176:179], v[228:231], v[74:77]
	v_mfma_f32_16x16x32_bf16 v[126:129], v[172:175], v[208:211], v[126:129]
	v_mfma_f32_16x16x32_bf16 v[122:125], v[180:183], v[208:211], v[122:125]
	v_mfma_f32_16x16x32_bf16 v[110:113], v[172:175], v[216:219], v[110:113]
	v_mfma_f32_16x16x32_bf16 v[106:109], v[180:183], v[216:219], v[106:109]
	v_mfma_f32_16x16x32_bf16 v[94:97], v[172:175], v[224:227], v[94:97]
	v_mfma_f32_16x16x32_bf16 v[90:93], v[180:183], v[224:227], v[90:93]
	v_mfma_f32_16x16x32_bf16 v[78:81], v[172:175], v[232:235], v[78:81]
	v_mfma_f32_16x16x32_bf16 v[74:77], v[180:183], v[232:235], v[74:77]
	s_setprio 0
	s_setprio 1
	v_mfma_f32_16x16x32_bf16 v[118:121], v[184:187], v[204:207], v[118:121]
	v_mfma_f32_16x16x32_bf16 v[114:117], v[196:199], v[204:207], v[114:117]
	v_mfma_f32_16x16x32_bf16 v[102:105], v[184:187], v[212:215], v[102:105]
	v_mfma_f32_16x16x32_bf16 v[98:101], v[196:199], v[212:215], v[98:101]
	v_mfma_f32_16x16x32_bf16 v[86:89], v[184:187], v[220:223], v[86:89]
	v_mfma_f32_16x16x32_bf16 v[82:85], v[196:199], v[220:223], v[82:85]
	v_mfma_f32_16x16x32_bf16 v[70:73], v[184:187], v[228:231], v[70:73]
	v_mfma_f32_16x16x32_bf16 v[66:69], v[196:199], v[228:231], v[66:69]
	v_mfma_f32_16x16x32_bf16 v[118:121], v[192:195], v[208:211], v[118:121]
	v_mfma_f32_16x16x32_bf16 v[114:117], v[200:203], v[208:211], v[114:117]
	v_mfma_f32_16x16x32_bf16 v[102:105], v[192:195], v[216:219], v[102:105]
	v_mfma_f32_16x16x32_bf16 v[98:101], v[200:203], v[216:219], v[98:101]
	v_mfma_f32_16x16x32_bf16 v[86:89], v[192:195], v[224:227], v[86:89]
	v_mfma_f32_16x16x32_bf16 v[82:85], v[200:203], v[224:227], v[82:85]
	v_mfma_f32_16x16x32_bf16 v[70:73], v[192:195], v[232:235], v[70:73]
	v_mfma_f32_16x16x32_bf16 v[66:69], v[200:203], v[232:235], v[66:69]
	s_setprio 0
	s_barrier
	s_add_i32 s15, s15, s50
	v_lshl_add_u64 v[154:155], v[154:155], 0, s[8:9]
	s_mov_b32 m0, s15
	ds_read_b128 v[204:207], v167 offset:49152
	ds_read_b128 v[208:211], v167 offset:50176
	ds_read_b128 v[212:215], v167 offset:51200
	ds_read_b128 v[216:219], v167 offset:52224
	ds_read_b128 v[220:223], v167 offset:53248
	ds_read_b128 v[224:227], v167 offset:54272
	ds_read_b128 v[228:231], v167 offset:55296
	ds_read_b128 v[232:235], v167 offset:56320
	global_load_lds_dwordx4 v[154:155], off
	s_add_i32 m0, s15, 0x2000
	s_add_u32 s18, s40, 0x40080
	v_lshl_add_u64 v[154:155], v[158:159], 0, s[8:9]
	s_addc_u32 s19, s41, 0
	s_add_i32 s15, s67, s50
	global_load_lds_dwordx4 v[154:155], off
	v_lshl_add_u64 v[154:155], s[18:19], 0, v[132:133]
	s_mov_b32 m0, s15
	s_nop 0
	global_load_lds_dwordx4 v[154:155], off
	v_lshl_add_u64 v[154:155], s[18:19], 0, v[136:137]
	s_add_i32 m0, s15, 0x2000
	s_nop 0
	global_load_lds_dwordx4 v[154:155], off
	v_lshl_add_u64 v[154:155], v[164:165], 0, s[8:9]
	s_mov_b32 m0, s55
	s_nop 0
	global_load_lds_dwordx4 v[154:155], off
	v_lshl_add_u64 v[154:155], v[168:169], 0, s[8:9]
	s_mov_b32 m0, s56
	s_nop 0
	global_load_lds_dwordx4 v[154:155], off
	s_waitcnt vmcnt(8)
	s_waitcnt lgkmcnt(0)
	s_barrier
	s_setprio 1
	s_waitcnt lgkmcnt(0)
	v_mfma_f32_16x16x32_bf16 v[62:65], v[150:153], v[204:207], v[62:65]
	v_mfma_f32_16x16x32_bf16 v[58:61], v[176:179], v[204:207], v[58:61]
	v_mfma_f32_16x16x32_bf16 v[46:49], v[150:153], v[212:215], v[46:49]
	v_mfma_f32_16x16x32_bf16 v[42:45], v[176:179], v[212:215], v[42:45]
	v_mfma_f32_16x16x32_bf16 v[30:33], v[150:153], v[220:223], v[30:33]
	v_mfma_f32_16x16x32_bf16 v[26:29], v[176:179], v[220:223], v[26:29]
	v_mfma_f32_16x16x32_bf16 v[14:17], v[150:153], v[228:231], v[14:17]
	v_mfma_f32_16x16x32_bf16 v[10:13], v[176:179], v[228:231], v[10:13]
	v_mfma_f32_16x16x32_bf16 v[62:65], v[172:175], v[208:211], v[62:65]
	v_mfma_f32_16x16x32_bf16 v[58:61], v[180:183], v[208:211], v[58:61]
	v_mfma_f32_16x16x32_bf16 v[46:49], v[172:175], v[216:219], v[46:49]
	v_mfma_f32_16x16x32_bf16 v[42:45], v[180:183], v[216:219], v[42:45]
	v_mfma_f32_16x16x32_bf16 v[30:33], v[172:175], v[224:227], v[30:33]
	v_mfma_f32_16x16x32_bf16 v[26:29], v[180:183], v[224:227], v[26:29]
	v_mfma_f32_16x16x32_bf16 v[14:17], v[172:175], v[232:235], v[14:17]
	v_mfma_f32_16x16x32_bf16 v[10:13], v[180:183], v[232:235], v[10:13]
	s_setprio 0
	s_setprio 1
	v_mfma_f32_16x16x32_bf16 v[54:57], v[184:187], v[204:207], v[54:57]
	v_mfma_f32_16x16x32_bf16 v[50:53], v[196:199], v[204:207], v[50:53]
	v_mfma_f32_16x16x32_bf16 v[38:41], v[184:187], v[212:215], v[38:41]
	v_mfma_f32_16x16x32_bf16 v[34:37], v[196:199], v[212:215], v[34:37]
	v_mfma_f32_16x16x32_bf16 v[22:25], v[184:187], v[220:223], v[22:25]
	v_mfma_f32_16x16x32_bf16 v[18:21], v[196:199], v[220:223], v[18:21]
	v_mfma_f32_16x16x32_bf16 v[6:9], v[184:187], v[228:231], v[6:9]
	v_mfma_f32_16x16x32_bf16 v[2:5], v[196:199], v[228:231], v[2:5]
	v_mfma_f32_16x16x32_bf16 v[54:57], v[192:195], v[208:211], v[54:57]
	v_mfma_f32_16x16x32_bf16 v[50:53], v[200:203], v[208:211], v[50:53]
	v_mfma_f32_16x16x32_bf16 v[38:41], v[192:195], v[216:219], v[38:41]
	v_mfma_f32_16x16x32_bf16 v[34:37], v[200:203], v[216:219], v[34:37]
	v_mfma_f32_16x16x32_bf16 v[22:25], v[192:195], v[224:227], v[22:25]
	v_mfma_f32_16x16x32_bf16 v[18:21], v[200:203], v[224:227], v[18:21]
	v_mfma_f32_16x16x32_bf16 v[6:9], v[192:195], v[232:235], v[6:9]
	v_mfma_f32_16x16x32_bf16 v[2:5], v[200:203], v[232:235], v[2:5]
	s_setprio 0
	s_barrier
	s_add_i32 s66, s66, 2
	s_add_u32 s64, s64, 0x100
	s_addc_u32 s65, s65, 0
	s_add_u32 s38, s38, 0x100
	s_addc_u32 s39, s39, 0

; __device__ __forceinline__ u32x4 pack8(const f32x4 a, const f32x4 b) { u32x4 w; w.x = pk2(a[0], a[1]); w.y = pk2(a[2], a[3]); w.z = pk2(b[0], b[1]); w.w = pk2(b[2], b[3]); return w; }
;     __device__ __forceinline__ void operator()(const Acc& acc, const Unit& u, int wr, int wc, int fr, int fq) const {
;         const int row0 = u.pm * 256 + wr * 64 + fr;
;         float rs[8]; rstd8(ssq, row0, fq, rs);
; #pragma unroll
;         for (int ai = 0; ai < 2; ++ai)
; #pragma unroll
;             for (int m = 0; m < 4; ++m) {
;                 const int row = row0 + ai * 128 + m * 16; const float r1 = rs[ai * 4 + m];
;                 f32x4 o[2];
; #pragma unroll
;                 for (int n = 0; n < 2; ++n) {
;                     const f32x4 gs = acc[ai][0][m][n] * r1, us = acc[ai][1][m][n] * r1, t = gs * -1.4426950408889634f;
;                     f32x4 d; d[0] = __builtin_amdgcn_exp2f(t[0]); d[1] = __builtin_amdgcn_exp2f(t[1]); d[2] = __builtin_amdgcn_exp2f(t[2]); d[3] = __builtin_amdgcn_exp2f(t[3]);
;                     d = d + 1.0f;
;                     f32x4 r; r[0] = __builtin_amdgcn_rcpf(d[0]); r[1] = __builtin_amdgcn_rcpf(d[1]); r[2] = __builtin_amdgcn_rcpf(d[2]); r[3] = __builtin_amdgcn_rcpf(d[3]);
;                     o[n] = (gs * us) * r;
;                 }
;                 *(u32x4*)(hid + (size_t)row * FF + u.pn * 128 + wc * 32 + 8 * fq) = pack8(o[0], o[1]);
.LBB0_342:
	v_lshl_add_u32 v176, s36, 8, v1
	v_ashrrev_i32_e32 v177, 31, v176
	v_or_b32_e32 v172, 16, v176
	v_lshlrev_b64 v[150:151], 6, v[176:177]
	v_ashrrev_i32_e32 v173, 31, v172
	v_or_b32_e32 v168, 32, v176
	v_lshl_add_u64 v[150:151], v[140:141], 0, v[150:151]
	v_lshlrev_b64 v[152:153], 6, v[172:173]
	v_ashrrev_i32_e32 v169, 31, v168
	v_or_b32_e32 v164, 48, v176
	v_lshl_add_u64 v[152:153], v[140:141], 0, v[152:153]
	v_lshlrev_b64 v[150:151], 6, v[168:169]
	v_ashrrev_i32_e32 v165, 31, v164
	v_add_u32_e32 v158, 0x80, v176
	v_lshl_add_u64 v[150:151], v[140:141], 0, v[150:151]
	v_lshlrev_b64 v[152:153], 6, v[164:165]
	v_ashrrev_i32_e32 v159, 31, v158
	v_lshl_add_u64 v[152:153], v[140:141], 0, v[152:153]
	v_lshlrev_b64 v[150:151], 6, v[158:159]
	v_lshl_add_u64 v[150:151], v[140:141], 0, v[150:151]
	v_add_u32_e32 v154, 0x90, v176
	v_ashrrev_i32_e32 v155, 31, v154
	v_lshlrev_b64 v[150:151], 6, v[154:155]
	v_lshl_add_u64 v[150:151], v[140:141], 0, v[150:151]
	v_add_u32_e32 v152, 0xa0, v176
	v_add_u32_e32 v150, 0xb0, v176
	v_ashrrev_i32_e32 v153, 31, v152
	v_ashrrev_i32_e32 v151, 31, v150
	v_lshlrev_b64 v[174:175], 6, v[152:153]
	v_lshlrev_b64 v[204:205], 6, v[150:151]
	v_lshl_add_u64 v[174:175], v[140:141], 0, v[174:175]
	v_lshl_add_u64 v[208:209], v[140:141], 0, v[204:205]
	s_nop 0
	s_andn2_b64 vcc, exec, s[2:3]
	s_mov_b64 s[2:3], -1
	v_mov_b32_e32 v178, v243
	v_pk_mul_f32 v[126:127], v[126:127], v[178:179] op_sel_hi:[1,0]
	v_pk_mul_f32 v[128:129], v[128:129], v[178:179] op_sel_hi:[1,0]
	v_pk_mul_f32 v[120:121], v[120:121], v[178:179] op_sel_hi:[1,0]
	v_pk_mul_f32 v[122:123], v[122:123], v[178:179] op_sel_hi:[1,0]
	v_pk_mul_f32 v[182:183], v[128:129], s[24:25] op_sel_hi:[1,0]
	v_pk_mul_f32 v[184:185], v[126:127], s[24:25] op_sel_hi:[1,0]
	v_pk_mul_f32 v[118:119], v[118:119], v[178:179] op_sel_hi:[1,0]
	v_pk_mul_f32 v[120:121], v[128:129], v[120:121]
	v_pk_mul_f32 v[124:125], v[124:125], v[178:179] op_sel_hi:[1,0]
	v_pk_mul_f32 v[128:129], v[122:123], s[24:25] op_sel_hi:[1,0]
	v_exp_f32_e32 v184, v184
	v_exp_f32_e32 v185, v185
	v_pk_mul_f32 v[118:119], v[126:127], v[118:119]
	v_pk_mul_f32 v[126:127], v[124:125], s[24:25] op_sel_hi:[1,0]
	v_exp_f32_e32 v128, v128
	v_exp_f32_e32 v129, v129
	v_exp_f32_e32 v182, v182
	v_exp_f32_e32 v183, v183
	v_exp_f32_e32 v126, v126
	v_exp_f32_e32 v127, v127
	v_pk_add_f32 v[184:185], v[184:185], 1.0 op_sel_hi:[1,0]
	v_pk_add_f32 v[128:129], v[128:129], 1.0 op_sel_hi:[1,0]
	v_pk_add_f32 v[182:183], v[182:183], 1.0 op_sel_hi:[1,0]
	v_rcp_f32_e32 v184, v184
	v_rcp_f32_e32 v185, v185
	v_pk_add_f32 v[126:127], v[126:127], 1.0 op_sel_hi:[1,0]
	v_rcp_f32_e32 v128, v128
	v_rcp_f32_e32 v129, v129
	v_rcp_f32_e32 v182, v182
	v_rcp_f32_e32 v183, v183
	v_rcp_f32_e32 v126, v126
	v_rcp_f32_e32 v127, v127
	v_pk_mul_f32 v[114:115], v[114:115], v[178:179] op_sel_hi:[1,0]
	v_pk_mul_f32 v[116:117], v[116:117], v[178:179] op_sel_hi:[1,0]
	v_pk_mul_f32 v[114:115], v[122:123], v[114:115]
	v_pk_mul_f32 v[118:119], v[118:119], v[184:185]
	v_pk_mul_f32 v[116:117], v[124:125], v[116:117]
	v_pk_mul_f32 v[114:115], v[114:115], v[128:129]
	v_pk_mul_f32 v[120:121], v[120:121], v[182:183]
	v_pk_mul_f32 v[122:123], v[116:117], v[126:127]
	v_cvt_pk_bf16_f32 v116, v118, v119
	v_cvt_pk_bf16_f32 v117, v120, v121
	v_cvt_pk_bf16_f32 v118, v114, v115
	v_mov_b64_e32 v[114:115], s[6:7]
	v_mad_i64_i32 v[120:121], s[18:19], v176, s60, v[114:115]
	s_lshl_b32 s18, s37, 7
	v_mov_b32_e32 v180, v244
	s_ashr_i32 s19, s18, 31
	s_lshl_b64 s[36:37], s[18:19], 1
	v_lshl_add_u64 v[120:121], v[120:121], 0, s[36:37]
	v_lshl_add_u64 v[120:121], v[120:121], 0, s[0:1]
	v_cvt_pk_bf16_f32 v119, v122, v123
	v_lshl_add_u64 v[120:121], v[120:121], 0, v[138:139]
	v_pk_mul_f32 v[110:111], v[110:111], v[180:181] op_sel_hi:[1,0]
	global_store_dwordx4 v[120:121], v[116:119], off
	v_pk_mul_f32 v[112:113], v[112:113], v[180:181] op_sel_hi:[1,0]
	v_pk_mul_f32 v[104:105], v[104:105], v[180:181] op_sel_hi:[1,0]
	v_pk_mul_f32 v[118:119], v[110:111], s[24:25] op_sel_hi:[1,0]
	v_pk_mul_f32 v[102:103], v[102:103], v[180:181] op_sel_hi:[1,0]
	v_pk_mul_f32 v[106:107], v[106:107], v[180:181] op_sel_hi:[1,0]
	v_pk_mul_f32 v[108:109], v[108:109], v[180:181] op_sel_hi:[1,0]
	v_pk_mul_f32 v[116:117], v[112:113], s[24:25] op_sel_hi:[1,0]
	v_exp_f32_e32 v118, v118
	v_exp_f32_e32 v119, v119
	v_pk_mul_f32 v[102:103], v[110:111], v[102:103]
	v_pk_mul_f32 v[104:105], v[112:113], v[104:105]
	v_pk_mul_f32 v[110:111], v[108:109], s[24:25] op_sel_hi:[1,0]
	v_pk_mul_f32 v[112:113], v[106:107], s[24:25] op_sel_hi:[1,0]
	v_exp_f32_e32 v110, v110
	v_exp_f32_e32 v112, v112
	v_exp_f32_e32 v111, v111
	v_exp_f32_e32 v113, v113
	v_exp_f32_e32 v116, v116
	v_exp_f32_e32 v117, v117
	v_pk_add_f32 v[118:119], v[118:119], 1.0 op_sel_hi:[1,0]
	v_rcp_f32_e32 v118, v118
	v_rcp_f32_e32 v119, v119
	v_pk_add_f32 v[110:111], v[110:111], 1.0 op_sel_hi:[1,0]
	v_pk_add_f32 v[112:113], v[112:113], 1.0 op_sel_hi:[1,0]
	v_rcp_f32_e32 v112, v112
	v_rcp_f32_e32 v110, v110
	v_rcp_f32_e32 v111, v111
	v_rcp_f32_e32 v113, v113
	v_pk_add_f32 v[116:117], v[116:117], 1.0 op_sel_hi:[1,0]
	v_pk_mul_f32 v[100:101], v[100:101], v[180:181] op_sel_hi:[1,0]
	v_pk_mul_f32 v[98:99], v[98:99], v[180:181] op_sel_hi:[1,0]
	v_mov_b32_e32 v174, v245
	v_rcp_f32_e32 v116, v116
	v_rcp_f32_e32 v117, v117
	v_pk_mul_f32 v[102:103], v[102:103], v[118:119]
	v_pk_mul_f32 v[98:99], v[106:107], v[98:99]
	v_pk_mul_f32 v[100:101], v[108:109], v[100:101]
	v_pk_mul_f32 v[104:105], v[104:105], v[116:117]
	v_pk_mul_f32 v[106:107], v[100:101], v[110:111]
	v_pk_mul_f32 v[100:101], v[98:99], v[112:113]
	v_cvt_pk_bf16_f32 v98, v102, v103
	v_mad_i64_i32 v[102:103], s[18:19], v172, s60, v[114:115]
; __device__ __forceinline__ u32x4 pack8(const f32x4 a, const f32x4 b) { u32x4 w; w.x = pk2(a[0], a[1]); w.y = pk2(a[2], a[3]); w.z = pk2(b[0], b[1]); w.w = pk2(b[2], b[3]); return w; }
;     __device__ __forceinline__ void operator()(const Acc& acc, const Unit& u, int wr, int wc, int fr, int fq) const {
;     ...
;             for (int m = 0; m < 4; ++m) {
;                 const int row = row0 + ai * 128 + m * 16; const float r1 = rs[ai * 4 + m];
;                 f32x4 o[2];
; #pragma unroll
;                 for (int n = 0; n < 2; ++n) {
;                     const f32x4 gs = acc[ai][0][m][n] * r1, us = acc[ai][1][m][n] * r1, t = gs * -1.4426950408889634f;
;                     f32x4 d; d[0] = __builtin_amdgcn_exp2f(t[0]); d[1] = __builtin_amdgcn_exp2f(t[1]); d[2] = __builtin_amdgcn_exp2f(t[2]); d[3] = __builtin_amdgcn_exp2f(t[3]);
;                     d = d + 1.0f;
;                     f32x4 r; r[0] = __builtin_amdgcn_rcpf(d[0]); r[1] = __builtin_amdgcn_rcpf(d[1]); r[2] = __builtin_amdgcn_rcpf(d[2]); r[3] = __builtin_amdgcn_rcpf(d[3]);
;                     o[n] = (gs * us) * r;
;                 }
;                 *(u32x4*)(hid + (size_t)row * FF + u.pn * 128 + wc * 32 + 8 * fq) = pack8(o[0], o[1]);
	v_lshl_add_u64 v[102:103], v[102:103], 0, s[36:37]
	v_lshl_add_u64 v[102:103], v[102:103], 0, s[0:1]
	v_cvt_pk_bf16_f32 v99, v104, v105
	v_cvt_pk_bf16_f32 v100, v100, v101
	v_cvt_pk_bf16_f32 v101, v106, v107
	v_lshl_add_u64 v[102:103], v[102:103], 0, v[138:139]
	v_pk_mul_f32 v[94:95], v[94:95], v[174:175] op_sel_hi:[1,0]
	global_store_dwordx4 v[102:103], v[98:101], off
	v_pk_mul_f32 v[96:97], v[96:97], v[174:175] op_sel_hi:[1,0]
	v_pk_mul_f32 v[88:89], v[88:89], v[174:175] op_sel_hi:[1,0]
	v_pk_mul_f32 v[100:101], v[94:95], s[24:25] op_sel_hi:[1,0]
	v_pk_mul_f32 v[86:87], v[86:87], v[174:175] op_sel_hi:[1,0]
	v_pk_mul_f32 v[90:91], v[90:91], v[174:175] op_sel_hi:[1,0]
	v_pk_mul_f32 v[92:93], v[92:93], v[174:175] op_sel_hi:[1,0]
	v_pk_mul_f32 v[98:99], v[96:97], s[24:25] op_sel_hi:[1,0]
	v_exp_f32_e32 v100, v100
	v_exp_f32_e32 v101, v101
	v_pk_mul_f32 v[86:87], v[94:95], v[86:87]
	v_pk_mul_f32 v[88:89], v[96:97], v[88:89]
	v_pk_mul_f32 v[94:95], v[92:93], s[24:25] op_sel_hi:[1,0]
	v_pk_mul_f32 v[96:97], v[90:91], s[24:25] op_sel_hi:[1,0]
	v_exp_f32_e32 v94, v94
	v_exp_f32_e32 v96, v96
	v_exp_f32_e32 v95, v95
	v_exp_f32_e32 v97, v97
	v_exp_f32_e32 v98, v98
	v_exp_f32_e32 v99, v99
	v_pk_add_f32 v[100:101], v[100:101], 1.0 op_sel_hi:[1,0]
	v_rcp_f32_e32 v100, v100
	v_rcp_f32_e32 v101, v101
	v_pk_add_f32 v[94:95], v[94:95], 1.0 op_sel_hi:[1,0]
	v_pk_add_f32 v[96:97], v[96:97], 1.0 op_sel_hi:[1,0]
	v_rcp_f32_e32 v96, v96
	v_rcp_f32_e32 v94, v94
	v_rcp_f32_e32 v95, v95
	v_rcp_f32_e32 v97, v97
	v_pk_add_f32 v[98:99], v[98:99], 1.0 op_sel_hi:[1,0]
	v_pk_mul_f32 v[84:85], v[84:85], v[174:175] op_sel_hi:[1,0]
	v_pk_mul_f32 v[82:83], v[82:83], v[174:175] op_sel_hi:[1,0]
	v_mov_b32_e32 v170, v246
	v_rcp_f32_e32 v98, v98
	v_rcp_f32_e32 v99, v99
	v_pk_mul_f32 v[86:87], v[86:87], v[100:101]
	v_pk_mul_f32 v[82:83], v[90:91], v[82:83]
	v_pk_mul_f32 v[84:85], v[92:93], v[84:85]
	v_pk_mul_f32 v[88:89], v[88:89], v[98:99]
	v_pk_mul_f32 v[90:91], v[84:85], v[94:95]
	v_pk_mul_f32 v[84:85], v[82:83], v[96:97]
	v_cvt_pk_bf16_f32 v82, v86, v87
	v_mad_i64_i32 v[86:87], s[18:19], v168, s60, v[114:115]
	v_lshl_add_u64 v[86:87], v[86:87], 0, s[36:37]
	v_lshl_add_u64 v[86:87], v[86:87], 0, s[0:1]
	v_cvt_pk_bf16_f32 v83, v88, v89
	v_cvt_pk_bf16_f32 v84, v84, v85
	v_cvt_pk_bf16_f32 v85, v90, v91
	v_lshl_add_u64 v[86:87], v[86:87], 0, v[138:139]
	v_pk_mul_f32 v[78:79], v[78:79], v[170:171] op_sel_hi:[1,0]
	global_store_dwordx4 v[86:87], v[82:85], off
	v_pk_mul_f32 v[80:81], v[80:81], v[170:171] op_sel_hi:[1,0]
	v_pk_mul_f32 v[72:73], v[72:73], v[170:171] op_sel_hi:[1,0]
	v_pk_mul_f32 v[84:85], v[78:79], s[24:25] op_sel_hi:[1,0]
	v_pk_mul_f32 v[70:71], v[70:71], v[170:171] op_sel_hi:[1,0]
	v_pk_mul_f32 v[74:75], v[74:75], v[170:171] op_sel_hi:[1,0]
	v_pk_mul_f32 v[76:77], v[76:77], v[170:171] op_sel_hi:[1,0]
	v_pk_mul_f32 v[82:83], v[80:81], s[24:25] op_sel_hi:[1,0]
	v_exp_f32_e32 v84, v84
	v_exp_f32_e32 v85, v85
	v_pk_mul_f32 v[70:71], v[78:79], v[70:71]
	v_pk_mul_f32 v[72:73], v[80:81], v[72:73]
	v_pk_mul_f32 v[78:79], v[76:77], s[24:25] op_sel_hi:[1,0]
	v_pk_mul_f32 v[80:81], v[74:75], s[24:25] op_sel_hi:[1,0]
	v_exp_f32_e32 v78, v78
	v_exp_f32_e32 v80, v80
	v_exp_f32_e32 v79, v79
	v_exp_f32_e32 v81, v81
	v_exp_f32_e32 v82, v82
	v_exp_f32_e32 v83, v83
	v_pk_add_f32 v[84:85], v[84:85], 1.0 op_sel_hi:[1,0]
	v_rcp_f32_e32 v84, v84
	v_rcp_f32_e32 v85, v85
	v_pk_add_f32 v[78:79], v[78:79], 1.0 op_sel_hi:[1,0]
	v_pk_add_f32 v[80:81], v[80:81], 1.0 op_sel_hi:[1,0]
	v_rcp_f32_e32 v80, v80
	v_rcp_f32_e32 v78, v78
	v_rcp_f32_e32 v79, v79
	v_rcp_f32_e32 v81, v81
	v_pk_add_f32 v[82:83], v[82:83], 1.0 op_sel_hi:[1,0]
	v_pk_mul_f32 v[68:69], v[68:69], v[170:171] op_sel_hi:[1,0]
	v_pk_mul_f32 v[66:67], v[66:67], v[170:171] op_sel_hi:[1,0]
	v_mov_b32_e32 v166, v247
	v_rcp_f32_e32 v82, v82
	v_rcp_f32_e32 v83, v83
	v_pk_mul_f32 v[70:71], v[70:71], v[84:85]
	v_pk_mul_f32 v[66:67], v[74:75], v[66:67]
	v_pk_mul_f32 v[68:69], v[76:77], v[68:69]
	v_pk_mul_f32 v[72:73], v[72:73], v[82:83]
	v_pk_mul_f32 v[74:75], v[68:69], v[78:79]
	v_pk_mul_f32 v[68:69], v[66:67], v[80:81]
	v_cvt_pk_bf16_f32 v66, v70, v71
	v_mad_i64_i32 v[70:71], s[18:19], v164, s60, v[114:115]
	v_lshl_add_u64 v[70:71], v[70:71], 0, s[36:37]
	v_lshl_add_u64 v[70:71], v[70:71], 0, s[0:1]
	v_cvt_pk_bf16_f32 v67, v72, v73
	v_cvt_pk_bf16_f32 v68, v68, v69
	v_cvt_pk_bf16_f32 v69, v74, v75
	v_lshl_add_u64 v[70:71], v[70:71], 0, v[138:139]
	v_pk_mul_f32 v[62:63], v[62:63], v[166:167] op_sel_hi:[1,0]
	global_store_dwordx4 v[70:71], v[66:69], off
	v_pk_mul_f32 v[64:65], v[64:65], v[166:167] op_sel_hi:[1,0]
	v_pk_mul_f32 v[56:57], v[56:57], v[166:167] op_sel_hi:[1,0]
	v_pk_mul_f32 v[68:69], v[62:63], s[24:25] op_sel_hi:[1,0]
	v_pk_mul_f32 v[54:55], v[54:55], v[166:167] op_sel_hi:[1,0]
	v_pk_mul_f32 v[58:59], v[58:59], v[166:167] op_sel_hi:[1,0]
	v_pk_mul_f32 v[60:61], v[60:61], v[166:167] op_sel_hi:[1,0]
	v_pk_mul_f32 v[66:67], v[64:65], s[24:25] op_sel_hi:[1,0]
	v_exp_f32_e32 v68, v68
	v_exp_f32_e32 v69, v69
	v_pk_mul_f32 v[54:55], v[62:63], v[54:55]
	v_pk_mul_f32 v[56:57], v[64:65], v[56:57]
	v_pk_mul_f32 v[62:63], v[60:61], s[24:25] op_sel_hi:[1,0]
	v_pk_mul_f32 v[64:65], v[58:59], s[24:25] op_sel_hi:[1,0]
	v_exp_f32_e32 v64, v64
	v_exp_f32_e32 v62, v62
	v_exp_f32_e32 v63, v63
	v_exp_f32_e32 v65, v65
	v_exp_f32_e32 v66, v66
	v_exp_f32_e32 v67, v67
	v_pk_add_f32 v[68:69], v[68:69], 1.0 op_sel_hi:[1,0]
	v_rcp_f32_e32 v68, v68
	v_rcp_f32_e32 v69, v69
	v_pk_add_f32 v[62:63], v[62:63], 1.0 op_sel_hi:[1,0]
	v_pk_add_f32 v[64:65], v[64:65], 1.0 op_sel_hi:[1,0]
	v_rcp_f32_e32 v64, v64
	v_rcp_f32_e32 v62, v62
	v_rcp_f32_e32 v63, v63
; __device__ __forceinline__ u32x4 pack8(const f32x4 a, const f32x4 b) { u32x4 w; w.x = pk2(a[0], a[1]); w.y = pk2(a[2], a[3]); w.z = pk2(b[0], b[1]); w.w = pk2(b[2], b[3]); return w; }
;     __device__ __forceinline__ void operator()(const Acc& acc, const Unit& u, int wr, int wc, int fr, int fq) const {
;     ...
;             for (int m = 0; m < 4; ++m) {
;                 const int row = row0 + ai * 128 + m * 16; const float r1 = rs[ai * 4 + m];
;                 f32x4 o[2];
; #pragma unroll
;                 for (int n = 0; n < 2; ++n) {
;                     const f32x4 gs = acc[ai][0][m][n] * r1, us = acc[ai][1][m][n] * r1, t = gs * -1.4426950408889634f;
;                     f32x4 d; d[0] = __builtin_amdgcn_exp2f(t[0]); d[1] = __builtin_amdgcn_exp2f(t[1]); d[2] = __builtin_amdgcn_exp2f(t[2]); d[3] = __builtin_amdgcn_exp2f(t[3]);
;                     d = d + 1.0f;
;                     f32x4 r; r[0] = __builtin_amdgcn_rcpf(d[0]); r[1] = __builtin_amdgcn_rcpf(d[1]); r[2] = __builtin_amdgcn_rcpf(d[2]); r[3] = __builtin_amdgcn_rcpf(d[3]);
;                     o[n] = (gs * us) * r;
;                 }
;                 *(u32x4*)(hid + (size_t)row * FF + u.pn * 128 + wc * 32 + 8 * fq) = pack8(o[0], o[1]);
	v_rcp_f32_e32 v65, v65
	v_pk_add_f32 v[66:67], v[66:67], 1.0 op_sel_hi:[1,0]
	v_pk_mul_f32 v[52:53], v[52:53], v[166:167] op_sel_hi:[1,0]
	v_pk_mul_f32 v[50:51], v[50:51], v[166:167] op_sel_hi:[1,0]
	v_mov_b32_e32 v162, v248
	v_rcp_f32_e32 v66, v66
	v_rcp_f32_e32 v67, v67
	v_pk_mul_f32 v[54:55], v[54:55], v[68:69]
	v_pk_mul_f32 v[50:51], v[58:59], v[50:51]
	v_pk_mul_f32 v[52:53], v[60:61], v[52:53]
	v_pk_mul_f32 v[56:57], v[56:57], v[66:67]
	v_pk_mul_f32 v[58:59], v[52:53], v[62:63]
	v_pk_mul_f32 v[52:53], v[50:51], v[64:65]
	v_cvt_pk_bf16_f32 v50, v54, v55
	v_mad_i64_i32 v[54:55], s[18:19], v158, s60, v[114:115]
	v_lshl_add_u64 v[54:55], v[54:55], 0, s[36:37]
	v_lshl_add_u64 v[54:55], v[54:55], 0, s[0:1]
	v_cvt_pk_bf16_f32 v51, v56, v57
	v_cvt_pk_bf16_f32 v52, v52, v53
	v_cvt_pk_bf16_f32 v53, v58, v59
	v_lshl_add_u64 v[54:55], v[54:55], 0, v[138:139]
	v_pk_mul_f32 v[46:47], v[46:47], v[162:163] op_sel_hi:[1,0]
	global_store_dwordx4 v[54:55], v[50:53], off
	v_pk_mul_f32 v[48:49], v[48:49], v[162:163] op_sel_hi:[1,0]
	v_pk_mul_f32 v[40:41], v[40:41], v[162:163] op_sel_hi:[1,0]
	v_pk_mul_f32 v[52:53], v[46:47], s[24:25] op_sel_hi:[1,0]
	v_pk_mul_f32 v[38:39], v[38:39], v[162:163] op_sel_hi:[1,0]
	v_pk_mul_f32 v[42:43], v[42:43], v[162:163] op_sel_hi:[1,0]
	v_pk_mul_f32 v[44:45], v[44:45], v[162:163] op_sel_hi:[1,0]
	v_pk_mul_f32 v[50:51], v[48:49], s[24:25] op_sel_hi:[1,0]
	v_exp_f32_e32 v52, v52
	v_exp_f32_e32 v53, v53
	v_pk_mul_f32 v[38:39], v[46:47], v[38:39]
	v_pk_mul_f32 v[40:41], v[48:49], v[40:41]
	v_pk_mul_f32 v[46:47], v[44:45], s[24:25] op_sel_hi:[1,0]
	v_pk_mul_f32 v[48:49], v[42:43], s[24:25] op_sel_hi:[1,0]
	v_exp_f32_e32 v48, v48
	v_exp_f32_e32 v46, v46
	v_exp_f32_e32 v47, v47
	v_exp_f32_e32 v49, v49
	v_exp_f32_e32 v50, v50
	v_exp_f32_e32 v51, v51
	v_pk_add_f32 v[52:53], v[52:53], 1.0 op_sel_hi:[1,0]
	v_rcp_f32_e32 v52, v52
	v_rcp_f32_e32 v53, v53
	v_pk_add_f32 v[46:47], v[46:47], 1.0 op_sel_hi:[1,0]
	v_pk_add_f32 v[48:49], v[48:49], 1.0 op_sel_hi:[1,0]
	v_rcp_f32_e32 v48, v48
	v_rcp_f32_e32 v46, v46
	v_rcp_f32_e32 v47, v47
	v_rcp_f32_e32 v49, v49
	v_pk_add_f32 v[50:51], v[50:51], 1.0 op_sel_hi:[1,0]
	v_pk_mul_f32 v[36:37], v[36:37], v[162:163] op_sel_hi:[1,0]
	v_pk_mul_f32 v[34:35], v[34:35], v[162:163] op_sel_hi:[1,0]
	v_mov_b32_e32 v160, v249
	v_rcp_f32_e32 v50, v50
	v_rcp_f32_e32 v51, v51
	v_pk_mul_f32 v[38:39], v[38:39], v[52:53]
	v_pk_mul_f32 v[34:35], v[42:43], v[34:35]
	v_pk_mul_f32 v[36:37], v[44:45], v[36:37]
	v_pk_mul_f32 v[40:41], v[40:41], v[50:51]
	v_pk_mul_f32 v[42:43], v[36:37], v[46:47]
	v_pk_mul_f32 v[36:37], v[34:35], v[48:49]
	v_cvt_pk_bf16_f32 v34, v38, v39
	v_mad_i64_i32 v[38:39], s[18:19], v154, s60, v[114:115]
	v_lshl_add_u64 v[38:39], v[38:39], 0, s[36:37]
	v_lshl_add_u64 v[38:39], v[38:39], 0, s[0:1]
	v_cvt_pk_bf16_f32 v35, v40, v41
	v_cvt_pk_bf16_f32 v36, v36, v37
	v_cvt_pk_bf16_f32 v37, v42, v43
	v_lshl_add_u64 v[38:39], v[38:39], 0, v[138:139]
	v_pk_mul_f32 v[30:31], v[30:31], v[160:161] op_sel_hi:[1,0]
	global_store_dwordx4 v[38:39], v[34:37], off
	v_pk_mul_f32 v[32:33], v[32:33], v[160:161] op_sel_hi:[1,0]
	v_pk_mul_f32 v[24:25], v[24:25], v[160:161] op_sel_hi:[1,0]
	v_pk_mul_f32 v[36:37], v[30:31], s[24:25] op_sel_hi:[1,0]
	v_pk_mul_f32 v[22:23], v[22:23], v[160:161] op_sel_hi:[1,0]
	v_pk_mul_f32 v[26:27], v[26:27], v[160:161] op_sel_hi:[1,0]
	v_pk_mul_f32 v[28:29], v[28:29], v[160:161] op_sel_hi:[1,0]
	v_pk_mul_f32 v[34:35], v[32:33], s[24:25] op_sel_hi:[1,0]
	v_exp_f32_e32 v36, v36
	v_exp_f32_e32 v37, v37
	v_pk_mul_f32 v[22:23], v[30:31], v[22:23]
; __device__ __forceinline__ u32x4 pack8(const f32x4 a, const f32x4 b) { u32x4 w; w.x = pk2(a[0], a[1]); w.y = pk2(a[2], a[3]); w.z = pk2(b[0], b[1]); w.w = pk2(b[2], b[3]); return w; }
; template <class Epi, class Sched, bool ALIGN_EPI = false, bool SP2 = false>
; __device__ __forceinline__ void gemm_phase(PG8_LAS unsigned char* lds, const Gemm g, const Sched& S, const Epi& E, const int tid) {
;     ...
;         if constexpr (!Epi::AFTER_DRAIN) { E(acc, cur, wr, wc, fr, fq); S.done(cur); }
;         if (!has_next) break;
;     __device__ __forceinline__ void operator()(const Acc& acc, const Unit& u, int wr, int wc, int fr, int fq) const {
;     ...
;             for (int m = 0; m < 4; ++m) {
;                 const int row = row0 + ai * 128 + m * 16; const float r1 = rs[ai * 4 + m];
;                 f32x4 o[2];
; #pragma unroll
;                 for (int n = 0; n < 2; ++n) {
;                     const f32x4 gs = acc[ai][0][m][n] * r1, us = acc[ai][1][m][n] * r1, t = gs * -1.4426950408889634f;
;                     f32x4 d; d[0] = __builtin_amdgcn_exp2f(t[0]); d[1] = __builtin_amdgcn_exp2f(t[1]); d[2] = __builtin_amdgcn_exp2f(t[2]); d[3] = __builtin_amdgcn_exp2f(t[3]);
;                     d = d + 1.0f;
;                     f32x4 r; r[0] = __builtin_amdgcn_rcpf(d[0]); r[1] = __builtin_amdgcn_rcpf(d[1]); r[2] = __builtin_amdgcn_rcpf(d[2]); r[3] = __builtin_amdgcn_rcpf(d[3]);
;                     o[n] = (gs * us) * r;
;                 }
;                 *(u32x4*)(hid + (size_t)row * FF + u.pn * 128 + wc * 32 + 8 * fq) = pack8(o[0], o[1]);
	v_pk_mul_f32 v[24:25], v[32:33], v[24:25]
	v_pk_mul_f32 v[30:31], v[28:29], s[24:25] op_sel_hi:[1,0]
	v_pk_mul_f32 v[32:33], v[26:27], s[24:25] op_sel_hi:[1,0]
	v_exp_f32_e32 v32, v32
	v_exp_f32_e32 v30, v30
	v_exp_f32_e32 v31, v31
	v_exp_f32_e32 v33, v33
	v_exp_f32_e32 v34, v34
	v_exp_f32_e32 v35, v35
	v_pk_add_f32 v[36:37], v[36:37], 1.0 op_sel_hi:[1,0]
	v_rcp_f32_e32 v36, v36
	v_rcp_f32_e32 v37, v37
	v_pk_add_f32 v[30:31], v[30:31], 1.0 op_sel_hi:[1,0]
	v_pk_add_f32 v[32:33], v[32:33], 1.0 op_sel_hi:[1,0]
	v_rcp_f32_e32 v32, v32
	v_rcp_f32_e32 v30, v30
	v_rcp_f32_e32 v31, v31
	v_rcp_f32_e32 v33, v33
	v_pk_add_f32 v[34:35], v[34:35], 1.0 op_sel_hi:[1,0]
	v_pk_mul_f32 v[20:21], v[20:21], v[160:161] op_sel_hi:[1,0]
	v_pk_mul_f32 v[18:19], v[18:19], v[160:161] op_sel_hi:[1,0]
	v_mov_b32_e32 v156, v250
	v_rcp_f32_e32 v34, v34
	v_rcp_f32_e32 v35, v35
	v_pk_mul_f32 v[22:23], v[22:23], v[36:37]
	v_pk_mul_f32 v[18:19], v[26:27], v[18:19]
	v_pk_mul_f32 v[20:21], v[28:29], v[20:21]
	v_pk_mul_f32 v[24:25], v[24:25], v[34:35]
	v_pk_mul_f32 v[26:27], v[20:21], v[30:31]
	v_pk_mul_f32 v[20:21], v[18:19], v[32:33]
	v_cvt_pk_bf16_f32 v18, v22, v23
	v_mad_i64_i32 v[22:23], s[18:19], v152, s60, v[114:115]
	v_lshl_add_u64 v[22:23], v[22:23], 0, s[36:37]
	v_lshl_add_u64 v[22:23], v[22:23], 0, s[0:1]
	v_cvt_pk_bf16_f32 v19, v24, v25
	v_cvt_pk_bf16_f32 v20, v20, v21
	v_cvt_pk_bf16_f32 v21, v26, v27
	v_lshl_add_u64 v[22:23], v[22:23], 0, v[138:139]
	v_pk_mul_f32 v[14:15], v[14:15], v[156:157] op_sel_hi:[1,0]
	global_store_dwordx4 v[22:23], v[18:21], off
	v_pk_mul_f32 v[16:17], v[16:17], v[156:157] op_sel_hi:[1,0]
	v_pk_mul_f32 v[8:9], v[8:9], v[156:157] op_sel_hi:[1,0]
	v_pk_mul_f32 v[20:21], v[14:15], s[24:25] op_sel_hi:[1,0]
	v_pk_mul_f32 v[6:7], v[6:7], v[156:157] op_sel_hi:[1,0]
	v_pk_mul_f32 v[10:11], v[10:11], v[156:157] op_sel_hi:[1,0]
	v_pk_mul_f32 v[12:13], v[12:13], v[156:157] op_sel_hi:[1,0]
	v_pk_mul_f32 v[18:19], v[16:17], s[24:25] op_sel_hi:[1,0]
	v_exp_f32_e32 v20, v20
	v_exp_f32_e32 v21, v21
	v_pk_mul_f32 v[6:7], v[14:15], v[6:7]
	v_pk_mul_f32 v[8:9], v[16:17], v[8:9]
	v_pk_mul_f32 v[14:15], v[12:13], s[24:25] op_sel_hi:[1,0]
	v_pk_mul_f32 v[16:17], v[10:11], s[24:25] op_sel_hi:[1,0]
	v_exp_f32_e32 v14, v14
	v_exp_f32_e32 v16, v16
	v_exp_f32_e32 v15, v15
	v_exp_f32_e32 v17, v17
	v_pk_add_f32 v[20:21], v[20:21], 1.0 op_sel_hi:[1,0]
	v_exp_f32_e32 v18, v18
	v_exp_f32_e32 v19, v19
	v_rcp_f32_e32 v20, v20
	v_rcp_f32_e32 v21, v21
	v_pk_add_f32 v[14:15], v[14:15], 1.0 op_sel_hi:[1,0]
	v_pk_add_f32 v[16:17], v[16:17], 1.0 op_sel_hi:[1,0]
	v_rcp_f32_e32 v14, v14
	v_rcp_f32_e32 v16, v16
	v_rcp_f32_e32 v15, v15
	v_rcp_f32_e32 v17, v17
	v_pk_mul_f32 v[4:5], v[4:5], v[156:157] op_sel_hi:[1,0]
	v_pk_mul_f32 v[2:3], v[2:3], v[156:157] op_sel_hi:[1,0]
	v_pk_add_f32 v[18:19], v[18:19], 1.0 op_sel_hi:[1,0]
	v_pk_mul_f32 v[6:7], v[6:7], v[20:21]
	v_pk_mul_f32 v[2:3], v[10:11], v[2:3]
	v_pk_mul_f32 v[4:5], v[12:13], v[4:5]
	v_rcp_f32_e32 v18, v18
	v_rcp_f32_e32 v19, v19
	v_pk_mul_f32 v[10:11], v[4:5], v[14:15]
	v_pk_mul_f32 v[4:5], v[2:3], v[16:17]
	v_cvt_pk_bf16_f32 v2, v6, v7
	v_mad_i64_i32 v[6:7], s[18:19], v150, s60, v[114:115]
	v_lshl_add_u64 v[6:7], v[6:7], 0, s[36:37]
	v_lshl_add_u64 v[6:7], v[6:7], 0, s[0:1]
	v_lshl_add_u64 v[6:7], v[6:7], 0, v[138:139]
	v_pk_mul_f32 v[8:9], v[8:9], v[18:19]
	s_nop 0
	v_cvt_pk_bf16_f32 v3, v8, v9
	v_cvt_pk_bf16_f32 v4, v4, v5
	v_cvt_pk_bf16_f32 v5, v10, v11
	global_store_dwordx4 v[6:7], v[2:5], off
	s_cbranch_vccnz .LBB0_331
	s_andn2_b64 vcc, exec, s[4:5]
	s_cbranch_vccnz .LBB0_330
	s_barrier
	s_branch .LBB0_330

; __global__ void __launch_bounds__(NWAVES * 64, 2) mega_fwd(Args args) {
	.amdhsa_kernel _Z8mega_fwd4Args
		.amdhsa_group_segment_fixed_size 0
		.amdhsa_private_segment_fixed_size 0
		.amdhsa_kernarg_size 448
		.amdhsa_user_sgpr_count 2
		.amdhsa_user_sgpr_dispatch_ptr 0
		.amdhsa_user_sgpr_queue_ptr 0
		.amdhsa_user_sgpr_kernarg_segment_ptr 1
		.amdhsa_user_sgpr_dispatch_id 0
		.amdhsa_user_sgpr_kernarg_preload_length 0
		.amdhsa_user_sgpr_kernarg_preload_offset 0
		.amdhsa_user_sgpr_private_segment_size 0
		.amdhsa_uses_dynamic_stack 0
		.amdhsa_enable_private_segment 0
		.amdhsa_system_sgpr_workgroup_id_x 1
		.amdhsa_system_sgpr_workgroup_id_y 0
		.amdhsa_system_sgpr_workgroup_id_z 0
		.amdhsa_system_sgpr_workgroup_info 0
		.amdhsa_system_vgpr_workitem_id 2
		.amdhsa_next_free_vgpr 256
		.amdhsa_next_free_sgpr 98
		.amdhsa_accum_offset 256
		.amdhsa_reserve_vcc 1
		.amdhsa_float_round_mode_32 0
		.amdhsa_float_round_mode_16_64 0
		.amdhsa_float_denorm_mode_32 3
		.amdhsa_float_denorm_mode_16_64 3
		.amdhsa_dx10_clamp 1
		.amdhsa_ieee_mode 1
		.amdhsa_fp16_overflow 0
		.amdhsa_tg_split 0
		.amdhsa_exception_fp_ieee_invalid_op 0
		.amdhsa_exception_fp_denorm_src 0
		.amdhsa_exception_fp_ieee_div_zero 0
		.amdhsa_exception_fp_ieee_overflow 0
		.amdhsa_exception_fp_ieee_underflow 0
		.amdhsa_exception_fp_ieee_inexact 0
		.amdhsa_exception_int_div_zero 0
	.end_amdhsa_kernel

; __global__ void __launch_bounds__(NWAVES * 64, 2) mega_fwd(Args args) {
amdhsa.kernels:
  - .agpr_count:     0
    .args:
      - .offset:         0
        .size:           192
        .value_kind:     by_value
      - .offset:         192
        .size:           4
        .value_kind:     hidden_block_count_x
      - .offset:         196
        .size:           4
        .value_kind:     hidden_block_count_y
      - .offset:         200
        .size:           4
        .value_kind:     hidden_block_count_z
      - .offset:         204
        .size:           2
        .value_kind:     hidden_group_size_x
      - .offset:         206
        .size:           2
        .value_kind:     hidden_group_size_y
      - .offset:         208
        .size:           2
        .value_kind:     hidden_group_size_z
      - .offset:         210
        .size:           2
        .value_kind:     hidden_remainder_x
      - .offset:         212
        .size:           2
        .value_kind:     hidden_remainder_y
      - .offset:         214
        .size:           2
        .value_kind:     hidden_remainder_z
      - .offset:         232
        .size:           8
        .value_kind:     hidden_global_offset_x
      - .offset:         240
        .size:           8
        .value_kind:     hidden_global_offset_y
      - .offset:         248
        .size:           8
        .value_kind:     hidden_global_offset_z
      - .offset:         256
        .size:           2
        .value_kind:     hidden_grid_dims
      - .offset:         280
        .size:           8
        .value_kind:     hidden_multigrid_sync_arg
      - .offset:         312
        .size:           4
        .value_kind:     hidden_dynamic_lds_size
    .group_segment_fixed_size: 0
    .kernarg_segment_align: 8
    .kernarg_segment_size: 448
    .language:       OpenCL C
    .language_version:
      - 2
      - 0
    .max_flat_workgroup_size: 512
    .name:           _Z8mega_fwd4Args
    .private_segment_fixed_size: 0
    .sgpr_count:     104
    .sgpr_spill_count: 3
    .symbol:         _Z8mega_fwd4Args.kd
    .uniform_work_group_size: 1
    .uses_dynamic_stack: false
    .vgpr_count:     256
    .vgpr_spill_count: 0
    .wavefront_size: 64
